# G4 tail GEMM: per-row rs load issued at item start with the operand loads instead of after the K-split reduction
# speedup vs baseline: 1.0217x; 1.0061x over previous
.LBB0_1107:
	s_and_b32 s10, s5, 0x70
	v_or_b32_e32 v11, s10, v10
	v_lshlrev_b32_e32 v92, 2, v11
	global_load_dword v92, v92, s[70:71]
	s_and_b32 s10, s8, 0xffffffc0
	v_or_b32_e32 v12, s10, v6
	v_ashrrev_i32_e32 v13, 31, v12
	v_lshlrev_b64 v[12:13], 11, v[12:13]
	v_lshl_add_u64 v[64:65], v[4:5], 0, v[12:13]
	s_mov_b32 s11, 0x8000
	v_add_co_u32_e32 v72, vcc, s11, v64
	s_mov_b32 s11, 0x10000
	s_nop 0
	v_addc_co_u32_e32 v73, vcc, 0, v65, vcc
	v_add_co_u32_e32 v80, vcc, s11, v64
	s_mov_b32 s11, 0x18000
	s_nop 0
	v_addc_co_u32_e32 v81, vcc, 0, v65, vcc
	v_lshlrev_b32_e32 v2, 11, v11
	v_add_co_u32_e32 v88, vcc, s11, v64
	v_lshl_add_u64 v[56:57], v[0:1], 0, v[2:3]
	s_nop 0
	v_addc_co_u32_e32 v89, vcc, 0, v65, vcc
	global_load_dwordx4 v[12:15], v[56:57], off
	global_load_dwordx4 v[16:19], v[56:57], off offset:64
	global_load_dwordx4 v[20:23], v[64:65], off
	global_load_dwordx4 v[24:27], v[64:65], off offset:64
	global_load_dwordx4 v[28:31], v[72:73], off
	global_load_dwordx4 v[32:35], v[72:73], off offset:64
	global_load_dwordx4 v[36:39], v[80:81], off
	global_load_dwordx4 v[40:43], v[80:81], off offset:64
	global_load_dwordx4 v[44:47], v[88:89], off
	global_load_dwordx4 v[48:51], v[88:89], off offset:64
	global_load_dwordx4 v[52:55], v[56:57], off offset:128
	s_nop 0
	global_load_dwordx4 v[56:59], v[56:57], off offset:192
	s_nop 0
	global_load_dwordx4 v[60:63], v[64:65], off offset:128
	s_nop 0
	global_load_dwordx4 v[64:67], v[64:65], off offset:192
	s_nop 0
	global_load_dwordx4 v[68:71], v[72:73], off offset:128
	s_nop 0
	global_load_dwordx4 v[72:75], v[72:73], off offset:192
	s_nop 0
	global_load_dwordx4 v[76:79], v[80:81], off offset:128
	s_nop 0
	global_load_dwordx4 v[80:83], v[80:81], off offset:192
	s_nop 0
	global_load_dwordx4 v[84:87], v[88:89], off offset:128
	s_nop 0
	global_load_dwordx4 v[88:91], v[88:89], off offset:192
	s_waitcnt vmcnt(0)
	v_mfma_f32_16x16x32_bf16 v[20:23], v[20:23], v[12:15], 0
	v_add_u32_e32 v2, s4, v7
	s_andn2_b64 vcc, exec, s[2:3]
	v_mfma_f32_16x16x32_bf16 v[28:31], v[28:31], v[12:15], 0
	v_mfma_f32_16x16x32_bf16 v[36:39], v[36:39], v[12:15], 0
	v_mfma_f32_16x16x32_bf16 v[12:15], v[44:47], v[12:15], 0
	v_mfma_f32_16x16x32_bf16 v[20:23], v[24:27], v[16:19], v[20:23]
	v_mfma_f32_16x16x32_bf16 v[12:15], v[48:51], v[16:19], v[12:15]
	v_mfma_f32_16x16x32_bf16 v[24:27], v[32:35], v[16:19], v[28:31]
	v_mfma_f32_16x16x32_bf16 v[28:31], v[40:43], v[16:19], v[36:39]
	v_mfma_f32_16x16x32_bf16 v[16:19], v[60:63], v[52:55], v[20:23]
	v_mfma_f32_16x16x32_bf16 v[12:15], v[84:87], v[52:55], v[12:15]
	v_mfma_f32_16x16x32_bf16 v[20:23], v[68:71], v[52:55], v[24:27]
	v_mfma_f32_16x16x32_bf16 v[24:27], v[76:79], v[52:55], v[28:31]
	v_mfma_f32_16x16x32_bf16 v[16:19], v[64:67], v[56:59], v[16:19]
	v_mfma_f32_16x16x32_bf16 v[12:15], v[88:91], v[56:59], v[12:15]
	v_mfma_f32_16x16x32_bf16 v[20:23], v[72:75], v[56:59], v[20:23]
	v_mfma_f32_16x16x32_bf16 v[24:27], v[80:83], v[56:59], v[24:27]
	s_nop 4
	ds_write_b128 v2, v[16:19]
	s_nop 0
	ds_write_b128 v2, v[20:23] offset:1024
	ds_write_b128 v2, v[24:27] offset:2048
	ds_write_b128 v2, v[12:15] offset:3072
	s_waitcnt lgkmcnt(0)
	s_barrier
	s_cbranch_vccnz .LBB0_1106
	ds_read_b128 v[12:15], v8
	ds_read_b128 v[16:19], v8 offset:4096
	ds_read_b128 v[32:35], v8 offset:8192
	ds_read_b128 v[36:39], v8 offset:12288
	ds_read_b128 v[40:43], v8 offset:16384
	ds_read_b128 v[44:47], v8 offset:20480
	ds_read_b128 v[48:51], v8 offset:24576
	ds_read_b128 v[52:55], v8 offset:28672
	s_waitcnt lgkmcnt(6)
	v_pk_add_f32 v[18:19], v[14:15], v[18:19]
	v_pk_add_f32 v[16:17], v[12:13], v[16:17]
	s_waitcnt lgkmcnt(5)
	v_pk_add_f32 v[18:19], v[18:19], v[34:35]
	v_pk_add_f32 v[16:17], v[16:17], v[32:33]
	s_waitcnt lgkmcnt(4)
	v_pk_add_f32 v[18:19], v[18:19], v[38:39]
	v_pk_add_f32 v[16:17], v[16:17], v[36:37]
	s_waitcnt lgkmcnt(3)
	v_pk_add_f32 v[18:19], v[18:19], v[42:43]
	v_pk_add_f32 v[16:17], v[16:17], v[40:41]
	s_waitcnt lgkmcnt(2)
	v_pk_add_f32 v[18:19], v[18:19], v[46:47]
	v_pk_add_f32 v[16:17], v[16:17], v[44:45]
	s_waitcnt lgkmcnt(1)
	v_pk_add_f32 v[18:19], v[18:19], v[50:51]
	v_pk_add_f32 v[16:17], v[16:17], v[48:49]
	s_waitcnt lgkmcnt(0)
	v_pk_add_f32 v[14:15], v[18:19], v[54:55]
	v_pk_add_f32 v[12:13], v[16:17], v[52:53]
	v_add_u32_e32 v16, s10, v9
	v_ashrrev_i32_e32 v17, 31, v16
	s_waitcnt vmcnt(0)
	v_mul_f32_e32 v12, v92, v12
	v_mul_f32_e32 v13, v92, v13
	v_mul_f32_e32 v14, v92, v14
	v_mul_f32_e32 v2, v92, v15
	v_max_f32_e32 v12, 0, v12
	v_max_f32_e32 v13, 0, v13
	v_max_f32_e32 v14, 0, v14
	v_max_f32_e32 v15, 0, v2
	v_lshlrev_b32_e32 v2, 13, v11
	v_pk_mul_f32 v[12:13], v[12:13], v[12:13]
	v_pk_mul_f32 v[14:15], v[14:15], v[14:15]
	v_lshl_add_u64 v[18:19], s[94:95], 0, v[2:3]
	v_lshl_add_u64 v[16:17], v[16:17], 1, v[18:19]
	v_cvt_pk_bf16_f32 v12, v12, v13
	v_cvt_pk_bf16_f32 v13, v14, v15
	global_store_dwordx2 v[16:17], v[12:13], off
	s_branch .LBB0_1106
